# grid barrier: flat release (all workgroups poll the top-level generation word; per-XCD generation hop and its atomic removed)
# speedup vs baseline: 1.0020x; 1.0020x over previous
.LBB0_28:
	s_or_b64 exec, exec, s[2:3]
	v_cvt_f32_u32_e32 v4, v2
	s_waitcnt vmcnt(0)
	v_readfirstlane_b32 s2, v3
	v_sub_u32_e32 v3, 0, v2
	v_rcp_iflag_f32_e32 v4, v4
	v_add_u32_e32 v5, s2, v1
	v_mul_f32_e32 v4, 0x4f7ffffe, v4
	v_cvt_u32_f32_e32 v4, v4
	v_mul_lo_u32 v1, v3, v4
	v_mul_hi_u32 v1, v4, v1
	v_add_u32_e32 v1, v4, v1
	v_mul_hi_u32 v1, v5, v1
	v_mul_lo_u32 v3, v1, v2
	v_sub_u32_e32 v3, v5, v3
	v_add_u32_e32 v4, 1, v1
	v_cmp_ge_u32_e32 vcc, v3, v2
	s_nop 1
	v_cndmask_b32_e32 v1, v1, v4, vcc
	v_sub_u32_e32 v4, v3, v2
	v_cndmask_b32_e32 v3, v3, v4, vcc
	v_add_u32_e32 v4, 1, v1
	v_cmp_ge_u32_e32 vcc, v3, v2
	v_add_u32_e32 v3, 1, v5
	s_nop 0
	v_cndmask_b32_e32 v1, v1, v4, vcc
	v_mul_lo_u32 v4, v2, v1
	v_add_u32_e32 v2, v4, v2
	v_cmp_ne_u32_e32 vcc, v3, v2
	s_and_saveexec_b64 s[2:3], vcc
	s_xor_b64 s[2:3], exec, s[2:3]
	s_cbranch_execz .LBB0_42
	v_readlane_b32 s6, v254, 54
	v_readlane_b32 s7, v254, 55
	s_waitcnt lgkmcnt(0)
	s_nop 3
	global_load_dword v0, v157, s[6:7] sc1
	s_waitcnt vmcnt(0)
	v_cmp_eq_u32_e32 vcc, v0, v1
	s_and_saveexec_b64 s[6:7], vcc
	s_cbranch_execz .LBB0_41
	s_mov_b32 s9, 1
	s_mov_b64 s[18:19], 0
	s_branch .LBB0_32

.LBB0_36:
	v_readlane_b32 s24, v254, 54
	v_readlane_b32 s25, v254, 55
	s_add_i32 s9, s9, 1
	s_mov_b64 s[26:27], -1
	s_nop 2
	global_load_dword v0, v157, s[24:25] sc1
	s_waitcnt vmcnt(0)
	v_cmp_ne_u32_e32 vcc, v0, v1
	s_orn2_b64 s[24:25], vcc, exec
	s_branch .LBB0_31

.LBB0_59:
	s_or_b64 exec, exec, s[2:3]
	s_mov_b64 s[2:3], exec
	v_mbcnt_lo_u32_b32 v0, s2, 0
	v_mbcnt_hi_u32_b32 v0, s3, v0
	v_cmp_eq_u32_e32 vcc, 0, v0
	s_waitcnt vmcnt(0)
	buffer_inv sc1
	s_and_saveexec_b64 s[6:7], vcc
	s_cbranch_execz .LBB0_61
	s_bcnt1_i32_b64 s2, s[2:3]
	v_mov_b32_e32 v0, s2
	v_readlane_b32 s2, v254, 50
	v_readlane_b32 s3, v254, 51
	s_nop 4
.LBB0_61:
	s_or_b64 exec, exec, s[6:7]
	s_waitcnt vmcnt(0)
